# HGRN2 elementwise waves: decay chains E_i = E_(i-1)(1-k_i) and 1/E backwards as one fused packed fma each (no stored 1-k factors), one copy less in the lane-swap prefix; split 17:15
# speedup vs baseline: 1.0962x; 1.0022x over previous
.Lhg_rel0:
	s_or_b64 exec, exec, s[38:39]
	s_waitcnt vmcnt(16)
	v_lshlrev_b32_e32 v76, 16, v10
	v_and_b32_e32 v77, 0xffff0000, v10
	v_lshlrev_b32_e32 v78, 16, v11
	v_and_b32_e32 v79, 0xffff0000, v11
	v_lshlrev_b32_e32 v80, 16, v12
	v_and_b32_e32 v81, 0xffff0000, v12
	v_lshlrev_b32_e32 v82, 16, v13
	v_and_b32_e32 v83, 0xffff0000, v13
	v_lshlrev_b32_e32 v84, 16, v14
	v_and_b32_e32 v85, 0xffff0000, v14
	v_lshlrev_b32_e32 v86, 16, v15
	v_and_b32_e32 v87, 0xffff0000, v15
	v_lshlrev_b32_e32 v88, 16, v16
	v_and_b32_e32 v89, 0xffff0000, v16
	v_lshlrev_b32_e32 v90, 16, v17
	v_and_b32_e32 v91, 0xffff0000, v17
	v_lshlrev_b32_e32 v92, 16, v18
	v_and_b32_e32 v93, 0xffff0000, v18
	v_lshlrev_b32_e32 v94, 16, v19
	v_and_b32_e32 v95, 0xffff0000, v19
	v_lshlrev_b32_e32 v96, 16, v20
	v_and_b32_e32 v97, 0xffff0000, v20
	v_lshlrev_b32_e32 v98, 16, v21
	v_and_b32_e32 v99, 0xffff0000, v21
	v_lshlrev_b32_e32 v100, 16, v22
	v_and_b32_e32 v101, 0xffff0000, v22
	v_lshlrev_b32_e32 v102, 16, v23
	v_and_b32_e32 v103, 0xffff0000, v23
	v_lshlrev_b32_e32 v104, 16, v24
	v_and_b32_e32 v105, 0xffff0000, v24
	v_lshlrev_b32_e32 v106, 16, v25
	v_and_b32_e32 v107, 0xffff0000, v25
	v_pk_add_f32 v[140:141], v[76:77], 1.0 op_sel_hi:[1,0] neg_lo:[1,0] neg_hi:[1,0]
	v_pk_add_f32 v[142:143], v[78:79], 1.0 op_sel_hi:[1,0] neg_lo:[1,0] neg_hi:[1,0]
	v_pk_fma_f32 v[144:145], v[80:81], v[140:141], v[140:141] neg_lo:[1,0,0] neg_hi:[1,0,0]
	v_pk_fma_f32 v[146:147], v[82:83], v[142:143], v[142:143] neg_lo:[1,0,0] neg_hi:[1,0,0]
	v_pk_fma_f32 v[148:149], v[84:85], v[144:145], v[144:145] neg_lo:[1,0,0] neg_hi:[1,0,0]
	v_pk_fma_f32 v[150:151], v[86:87], v[146:147], v[146:147] neg_lo:[1,0,0] neg_hi:[1,0,0]
	v_pk_fma_f32 v[152:153], v[88:89], v[148:149], v[148:149] neg_lo:[1,0,0] neg_hi:[1,0,0]
	v_pk_fma_f32 v[154:155], v[90:91], v[150:151], v[150:151] neg_lo:[1,0,0] neg_hi:[1,0,0]
	v_pk_fma_f32 v[156:157], v[92:93], v[152:153], v[152:153] neg_lo:[1,0,0] neg_hi:[1,0,0]
	v_pk_fma_f32 v[158:159], v[94:95], v[154:155], v[154:155] neg_lo:[1,0,0] neg_hi:[1,0,0]
	v_pk_fma_f32 v[160:161], v[96:97], v[156:157], v[156:157] neg_lo:[1,0,0] neg_hi:[1,0,0]
	v_pk_fma_f32 v[162:163], v[98:99], v[158:159], v[158:159] neg_lo:[1,0,0] neg_hi:[1,0,0]
	v_pk_fma_f32 v[164:165], v[100:101], v[160:161], v[160:161] neg_lo:[1,0,0] neg_hi:[1,0,0]
	v_pk_fma_f32 v[166:167], v[102:103], v[162:163], v[162:163] neg_lo:[1,0,0] neg_hi:[1,0,0]
	v_pk_fma_f32 v[168:169], v[104:105], v[164:165], v[164:165] neg_lo:[1,0,0] neg_hi:[1,0,0]
	v_pk_fma_f32 v[170:171], v[106:107], v[166:167], v[166:167] neg_lo:[1,0,0] neg_hi:[1,0,0]
	v_lshlrev_b32_e32 v108, 16, v26
	v_and_b32_e32 v109, 0xffff0000, v26
	v_lshlrev_b32_e32 v110, 16, v27
	v_and_b32_e32 v111, 0xffff0000, v27
	v_lshlrev_b32_e32 v112, 16, v28
	v_and_b32_e32 v113, 0xffff0000, v28
	v_lshlrev_b32_e32 v114, 16, v29
	v_and_b32_e32 v115, 0xffff0000, v29
	v_lshlrev_b32_e32 v116, 16, v30
	v_and_b32_e32 v117, 0xffff0000, v30
	v_lshlrev_b32_e32 v118, 16, v31
	v_and_b32_e32 v119, 0xffff0000, v31
	v_lshlrev_b32_e32 v120, 16, v32
	v_and_b32_e32 v121, 0xffff0000, v32
	v_lshlrev_b32_e32 v122, 16, v33
	v_and_b32_e32 v123, 0xffff0000, v33
	v_lshlrev_b32_e32 v124, 16, v34
	v_and_b32_e32 v125, 0xffff0000, v34
	v_lshlrev_b32_e32 v126, 16, v35
	v_and_b32_e32 v127, 0xffff0000, v35
	v_lshlrev_b32_e32 v128, 16, v36
	v_and_b32_e32 v129, 0xffff0000, v36
	v_lshlrev_b32_e32 v130, 16, v37
	v_and_b32_e32 v131, 0xffff0000, v37
	v_lshlrev_b32_e32 v132, 16, v38
	v_and_b32_e32 v133, 0xffff0000, v38
	v_lshlrev_b32_e32 v134, 16, v39
	v_and_b32_e32 v135, 0xffff0000, v39
	v_lshlrev_b32_e32 v136, 16, v40
	v_and_b32_e32 v137, 0xffff0000, v40
	v_lshlrev_b32_e32 v138, 16, v41
	v_and_b32_e32 v139, 0xffff0000, v41
	global_load_dwordx2 v[10:11], v3, s[8:9]
	global_load_dwordx2 v[26:27], v2, s[8:9]
	s_add_u32 s8, s8, s10
	s_addc_u32 s9, s9, s11
	global_load_dwordx2 v[12:13], v3, s[8:9]
	global_load_dwordx2 v[28:29], v2, s[8:9]
	s_add_u32 s8, s8, s10
	s_addc_u32 s9, s9, s11
	global_load_dwordx2 v[14:15], v3, s[8:9]
	global_load_dwordx2 v[30:31], v2, s[8:9]
	s_add_u32 s8, s8, s10
	s_addc_u32 s9, s9, s11
	global_load_dwordx2 v[16:17], v3, s[8:9]
	global_load_dwordx2 v[32:33], v2, s[8:9]
	s_add_u32 s8, s8, s10
	s_addc_u32 s9, s9, s11
	global_load_dwordx2 v[18:19], v3, s[8:9]
	global_load_dwordx2 v[34:35], v2, s[8:9]
	s_add_u32 s8, s8, s10
	s_addc_u32 s9, s9, s11
	global_load_dwordx2 v[20:21], v3, s[8:9]
	global_load_dwordx2 v[36:37], v2, s[8:9]
	s_add_u32 s8, s8, s10
	s_addc_u32 s9, s9, s11
	global_load_dwordx2 v[22:23], v3, s[8:9]
	global_load_dwordx2 v[38:39], v2, s[8:9]
	s_add_u32 s8, s8, s10
	s_addc_u32 s9, s9, s11
	global_load_dwordx2 v[24:25], v3, s[8:9]
	global_load_dwordx2 v[40:41], v2, s[8:9]
	s_add_u32 s8, s8, s10
	s_addc_u32 s9, s9, s11
	s_cmp_lt_u32 s16, 63
	s_cselect_b32 s34, s12, s14
	s_cselect_b32 s35, s13, s15
	s_add_u32 s8, s8, s34
	s_addc_u32 s9, s9, s35
	s_add_i32 s16, s16, 1
	v_mov_b32_e32 v176, 1.0
	v_mov_b32_e32 v177, 1.0
	v_mov_b32_e32 v178, 1.0
	v_mov_b32_e32 v179, 1.0
	v_mul_f32_dpp v196, v168, v168 row_ror:8 row_mask:0xf bank_mask:0xf
	v_mul_f32_dpp v197, v169, v169 row_ror:8 row_mask:0xf bank_mask:0xf
	v_mul_f32_dpp v198, v170, v170 row_ror:8 row_mask:0xf bank_mask:0xf
	v_mul_f32_dpp v199, v171, v171 row_ror:8 row_mask:0xf bank_mask:0xf
	v_mov_b32_dpp v176, v168 row_shr:8 row_mask:0xf bank_mask:0xc
	v_mov_b32_dpp v177, v169 row_shr:8 row_mask:0xf bank_mask:0xc
	v_mov_b32_dpp v178, v170 row_shr:8 row_mask:0xf bank_mask:0xc
	v_mov_b32_dpp v179, v171 row_shr:8 row_mask:0xf bank_mask:0xc
	v_mov_b32_e32 v200, v196
	v_mov_b32_e32 v201, v197
	v_mov_b32_e32 v202, v198
	v_mov_b32_e32 v203, v199
	v_permlane16_swap_b32_e32 v196, v200
	v_permlane16_swap_b32_e32 v197, v201
	v_permlane16_swap_b32_e32 v198, v202
	v_permlane16_swap_b32_e32 v199, v203
	v_pk_mul_f32 v[204:205], v[196:197], v[200:201]
	v_pk_mul_f32 v[206:207], v[198:199], v[202:203]
	s_nop 1
	v_permlane32_swap_b32_e32 v200, v204
	v_permlane32_swap_b32_e32 v201, v205
	v_permlane32_swap_b32_e32 v202, v206
	v_permlane32_swap_b32_e32 v203, v207
	s_mov_b64 s[34:35], exec
	s_mov_b64 exec, 0xffff0000
	v_pk_mul_f32 v[176:177], v[176:177], v[196:197]
	v_pk_mul_f32 v[178:179], v[178:179], v[198:199]
	s_mov_b32 exec_lo, 0
	s_mov_b32 exec_hi, -1
	v_pk_mul_f32 v[176:177], v[176:177], v[200:201]
	v_pk_mul_f32 v[178:179], v[178:179], v[202:203]
	s_mov_b32 exec_hi, 0xffff0000
	v_pk_mul_f32 v[176:177], v[176:177], v[196:197]
	v_pk_mul_f32 v[178:179], v[178:179], v[198:199]
	s_mov_b64 exec, s[34:35]
	v_pk_mul_f32 v[188:189], v[176:177], v[168:169]
	v_pk_mul_f32 v[190:191], v[178:179], v[170:171]
	s_mov_b64 s[34:35], exec
	s_mov_b64 exec, s[30:31]
	ds_write_b128 v8, v[188:191]
	s_mov_b64 exec, s[34:35]
	v_max_f32_e32 v180, 0xda24260, v188
	v_max_f32_e32 v181, 0xda24260, v189
	v_max_f32_e32 v182, 0xda24260, v190
	v_max_f32_e32 v183, 0xda24260, v191
	v_rcp_f32_e32 v180, v180
	v_rcp_f32_e32 v181, v181
	v_rcp_f32_e32 v182, v182
	v_rcp_f32_e32 v183, v183
	v_pk_mul_f32 v[192:193], v[136:137], v[188:189]
	v_pk_mul_f32 v[194:195], v[138:139], v[190:191]
	v_pk_mul_f32 v[196:197], v[104:105], v[180:181]
	v_pk_mul_f32 v[198:199], v[106:107], v[182:183]
	v_cvt_pk_bf16_f32 v208, v192, v193
	v_cvt_pk_bf16_f32 v209, v194, v195
	v_cvt_pk_bf16_f32 v210, v196, v197
	v_cvt_pk_bf16_f32 v211, v198, v199
	v_pk_fma_f32 v[180:181], v[104:105], v[180:181], v[180:181] neg_lo:[1,0,0] neg_hi:[1,0,0]
	v_pk_fma_f32 v[182:183], v[106:107], v[182:183], v[182:183] neg_lo:[1,0,0] neg_hi:[1,0,0]
	v_pk_mul_f32 v[188:189], v[176:177], v[164:165]
	v_pk_mul_f32 v[190:191], v[178:179], v[166:167]
	v_pk_mul_f32 v[192:193], v[132:133], v[188:189]
	v_pk_mul_f32 v[194:195], v[134:135], v[190:191]
	v_pk_mul_f32 v[200:201], v[100:101], v[180:181]
	v_pk_mul_f32 v[202:203], v[102:103], v[182:183]
	v_cvt_pk_bf16_f32 v204, v192, v193
	v_cvt_pk_bf16_f32 v205, v194, v195
	v_cvt_pk_bf16_f32 v206, v200, v201
	v_cvt_pk_bf16_f32 v207, v202, v203
	ds_write2_b64 v4, v[204:205], v[208:209] offset0:216 offset1:252
	ds_write2_b64 v7, v[206:207], v[210:211] offset0:216 offset1:252
	v_pk_fma_f32 v[180:181], v[100:101], v[180:181], v[180:181] neg_lo:[1,0,0] neg_hi:[1,0,0]
	v_pk_fma_f32 v[182:183], v[102:103], v[182:183], v[182:183] neg_lo:[1,0,0] neg_hi:[1,0,0]
	v_pk_mul_f32 v[188:189], v[176:177], v[160:161]
	v_pk_mul_f32 v[190:191], v[178:179], v[162:163]
	v_pk_mul_f32 v[192:193], v[128:129], v[188:189]
	v_pk_mul_f32 v[194:195], v[130:131], v[190:191]
	v_pk_mul_f32 v[196:197], v[96:97], v[180:181]
	v_pk_mul_f32 v[198:199], v[98:99], v[182:183]
	v_cvt_pk_bf16_f32 v208, v192, v193
	v_cvt_pk_bf16_f32 v209, v194, v195
	v_cvt_pk_bf16_f32 v210, v196, v197
	v_cvt_pk_bf16_f32 v211, v198, v199
	v_pk_fma_f32 v[180:181], v[96:97], v[180:181], v[180:181] neg_lo:[1,0,0] neg_hi:[1,0,0]
	v_pk_fma_f32 v[182:183], v[98:99], v[182:183], v[182:183] neg_lo:[1,0,0] neg_hi:[1,0,0]
	v_pk_mul_f32 v[188:189], v[176:177], v[156:157]
	v_pk_mul_f32 v[190:191], v[178:179], v[158:159]
	v_pk_mul_f32 v[192:193], v[124:125], v[188:189]
	v_pk_mul_f32 v[194:195], v[126:127], v[190:191]
	v_pk_mul_f32 v[200:201], v[92:93], v[180:181]
	v_pk_mul_f32 v[202:203], v[94:95], v[182:183]
	v_cvt_pk_bf16_f32 v204, v192, v193
	v_cvt_pk_bf16_f32 v205, v194, v195
	v_cvt_pk_bf16_f32 v206, v200, v201
	v_cvt_pk_bf16_f32 v207, v202, v203
	ds_write2_b64 v4, v[204:205], v[208:209] offset0:144 offset1:180
	ds_write2_b64 v7, v[206:207], v[210:211] offset0:144 offset1:180
	v_pk_fma_f32 v[180:181], v[92:93], v[180:181], v[180:181] neg_lo:[1,0,0] neg_hi:[1,0,0]
	v_pk_fma_f32 v[182:183], v[94:95], v[182:183], v[182:183] neg_lo:[1,0,0] neg_hi:[1,0,0]
	v_pk_mul_f32 v[188:189], v[176:177], v[152:153]
	v_pk_mul_f32 v[190:191], v[178:179], v[154:155]
	v_pk_mul_f32 v[192:193], v[120:121], v[188:189]
	v_pk_mul_f32 v[194:195], v[122:123], v[190:191]
	v_pk_mul_f32 v[196:197], v[88:89], v[180:181]
	v_pk_mul_f32 v[198:199], v[90:91], v[182:183]
	v_cvt_pk_bf16_f32 v208, v192, v193
	v_cvt_pk_bf16_f32 v209, v194, v195
	v_cvt_pk_bf16_f32 v210, v196, v197
	v_cvt_pk_bf16_f32 v211, v198, v199
	v_pk_fma_f32 v[180:181], v[88:89], v[180:181], v[180:181] neg_lo:[1,0,0] neg_hi:[1,0,0]
	v_pk_fma_f32 v[182:183], v[90:91], v[182:183], v[182:183] neg_lo:[1,0,0] neg_hi:[1,0,0]
	v_pk_mul_f32 v[188:189], v[176:177], v[148:149]
	v_pk_mul_f32 v[190:191], v[178:179], v[150:151]
	v_pk_mul_f32 v[192:193], v[116:117], v[188:189]
	v_pk_mul_f32 v[194:195], v[118:119], v[190:191]
	v_pk_mul_f32 v[200:201], v[84:85], v[180:181]
	v_pk_mul_f32 v[202:203], v[86:87], v[182:183]
	v_cvt_pk_bf16_f32 v204, v192, v193
	v_cvt_pk_bf16_f32 v205, v194, v195
	v_cvt_pk_bf16_f32 v206, v200, v201
	v_cvt_pk_bf16_f32 v207, v202, v203
	ds_write2_b64 v4, v[204:205], v[208:209] offset0:72 offset1:108
	ds_write2_b64 v7, v[206:207], v[210:211] offset0:72 offset1:108
	v_pk_fma_f32 v[180:181], v[84:85], v[180:181], v[180:181] neg_lo:[1,0,0] neg_hi:[1,0,0]
	v_pk_fma_f32 v[182:183], v[86:87], v[182:183], v[182:183] neg_lo:[1,0,0] neg_hi:[1,0,0]
	v_pk_mul_f32 v[188:189], v[176:177], v[144:145]
	v_pk_mul_f32 v[190:191], v[178:179], v[146:147]
	v_pk_mul_f32 v[192:193], v[112:113], v[188:189]
	v_pk_mul_f32 v[194:195], v[114:115], v[190:191]
	v_pk_mul_f32 v[196:197], v[80:81], v[180:181]
	v_pk_mul_f32 v[198:199], v[82:83], v[182:183]
	v_cvt_pk_bf16_f32 v208, v192, v193
	v_cvt_pk_bf16_f32 v209, v194, v195
	v_cvt_pk_bf16_f32 v210, v196, v197
	v_cvt_pk_bf16_f32 v211, v198, v199
	v_pk_fma_f32 v[180:181], v[80:81], v[180:181], v[180:181] neg_lo:[1,0,0] neg_hi:[1,0,0]
	v_pk_fma_f32 v[182:183], v[82:83], v[182:183], v[182:183] neg_lo:[1,0,0] neg_hi:[1,0,0]
	v_pk_mul_f32 v[188:189], v[176:177], v[140:141]
	v_pk_mul_f32 v[190:191], v[178:179], v[142:143]
	v_pk_mul_f32 v[192:193], v[108:109], v[188:189]
	v_pk_mul_f32 v[194:195], v[110:111], v[190:191]
	v_pk_mul_f32 v[200:201], v[76:77], v[180:181]
	v_pk_mul_f32 v[202:203], v[78:79], v[182:183]
	v_cvt_pk_bf16_f32 v204, v192, v193
	v_cvt_pk_bf16_f32 v205, v194, v195
	v_cvt_pk_bf16_f32 v206, v200, v201
	v_cvt_pk_bf16_f32 v207, v202, v203
	ds_write2_b64 v4, v[204:205], v[208:209] offset0:0 offset1:36
	ds_write2_b64 v7, v[206:207], v[210:211] offset0:0 offset1:36
	s_waitcnt vmcnt(16)
	v_lshlrev_b32_e32 v76, 16, v42
	v_and_b32_e32 v77, 0xffff0000, v42
	v_lshlrev_b32_e32 v78, 16, v43
	v_and_b32_e32 v79, 0xffff0000, v43
	v_lshlrev_b32_e32 v80, 16, v44
	v_and_b32_e32 v81, 0xffff0000, v44
	v_lshlrev_b32_e32 v82, 16, v45
	v_and_b32_e32 v83, 0xffff0000, v45
	v_lshlrev_b32_e32 v84, 16, v46
	v_and_b32_e32 v85, 0xffff0000, v46
	v_lshlrev_b32_e32 v86, 16, v47
	v_and_b32_e32 v87, 0xffff0000, v47
	v_lshlrev_b32_e32 v88, 16, v48
	v_and_b32_e32 v89, 0xffff0000, v48
	v_lshlrev_b32_e32 v90, 16, v49
	v_and_b32_e32 v91, 0xffff0000, v49
	v_lshlrev_b32_e32 v92, 16, v50
	v_and_b32_e32 v93, 0xffff0000, v50
	v_lshlrev_b32_e32 v94, 16, v51
	v_and_b32_e32 v95, 0xffff0000, v51
	v_lshlrev_b32_e32 v96, 16, v52
	v_and_b32_e32 v97, 0xffff0000, v52
	v_lshlrev_b32_e32 v98, 16, v53
	v_and_b32_e32 v99, 0xffff0000, v53
	v_lshlrev_b32_e32 v100, 16, v54
	v_and_b32_e32 v101, 0xffff0000, v54
	v_lshlrev_b32_e32 v102, 16, v55
	v_and_b32_e32 v103, 0xffff0000, v55
	v_lshlrev_b32_e32 v104, 16, v56
	v_and_b32_e32 v105, 0xffff0000, v56
	v_lshlrev_b32_e32 v106, 16, v57
	v_and_b32_e32 v107, 0xffff0000, v57
	v_pk_add_f32 v[140:141], v[76:77], 1.0 op_sel_hi:[1,0] neg_lo:[1,0] neg_hi:[1,0]
	v_pk_add_f32 v[142:143], v[78:79], 1.0 op_sel_hi:[1,0] neg_lo:[1,0] neg_hi:[1,0]
	v_pk_fma_f32 v[144:145], v[80:81], v[140:141], v[140:141] neg_lo:[1,0,0] neg_hi:[1,0,0]
	v_pk_fma_f32 v[146:147], v[82:83], v[142:143], v[142:143] neg_lo:[1,0,0] neg_hi:[1,0,0]
	v_pk_fma_f32 v[148:149], v[84:85], v[144:145], v[144:145] neg_lo:[1,0,0] neg_hi:[1,0,0]
	v_pk_fma_f32 v[150:151], v[86:87], v[146:147], v[146:147] neg_lo:[1,0,0] neg_hi:[1,0,0]
	v_pk_fma_f32 v[152:153], v[88:89], v[148:149], v[148:149] neg_lo:[1,0,0] neg_hi:[1,0,0]
	v_pk_fma_f32 v[154:155], v[90:91], v[150:151], v[150:151] neg_lo:[1,0,0] neg_hi:[1,0,0]
	v_pk_fma_f32 v[156:157], v[92:93], v[152:153], v[152:153] neg_lo:[1,0,0] neg_hi:[1,0,0]
	v_pk_fma_f32 v[158:159], v[94:95], v[154:155], v[154:155] neg_lo:[1,0,0] neg_hi:[1,0,0]
	v_pk_fma_f32 v[160:161], v[96:97], v[156:157], v[156:157] neg_lo:[1,0,0] neg_hi:[1,0,0]
	v_pk_fma_f32 v[162:163], v[98:99], v[158:159], v[158:159] neg_lo:[1,0,0] neg_hi:[1,0,0]
	v_pk_fma_f32 v[164:165], v[100:101], v[160:161], v[160:161] neg_lo:[1,0,0] neg_hi:[1,0,0]
	v_pk_fma_f32 v[166:167], v[102:103], v[162:163], v[162:163] neg_lo:[1,0,0] neg_hi:[1,0,0]
	v_pk_fma_f32 v[168:169], v[104:105], v[164:165], v[164:165] neg_lo:[1,0,0] neg_hi:[1,0,0]
	v_pk_fma_f32 v[170:171], v[106:107], v[166:167], v[166:167] neg_lo:[1,0,0] neg_hi:[1,0,0]
	s_waitcnt lgkmcnt(0)
	s_barrier
	s_mov_b32 s17, 31
.Lhg_ploop:
	v_lshlrev_b32_e32 v108, 16, v58
	v_and_b32_e32 v109, 0xffff0000, v58
	v_lshlrev_b32_e32 v110, 16, v59
	v_and_b32_e32 v111, 0xffff0000, v59
	v_lshlrev_b32_e32 v112, 16, v60
	v_and_b32_e32 v113, 0xffff0000, v60
	v_lshlrev_b32_e32 v114, 16, v61
	v_and_b32_e32 v115, 0xffff0000, v61
	v_lshlrev_b32_e32 v116, 16, v62
	v_and_b32_e32 v117, 0xffff0000, v62
	v_lshlrev_b32_e32 v118, 16, v63
	v_and_b32_e32 v119, 0xffff0000, v63
	v_lshlrev_b32_e32 v120, 16, v64
	v_and_b32_e32 v121, 0xffff0000, v64
	v_lshlrev_b32_e32 v122, 16, v65
	v_and_b32_e32 v123, 0xffff0000, v65
	v_lshlrev_b32_e32 v124, 16, v66
	v_and_b32_e32 v125, 0xffff0000, v66
	v_lshlrev_b32_e32 v126, 16, v67
	v_and_b32_e32 v127, 0xffff0000, v67
	v_lshlrev_b32_e32 v128, 16, v68
	v_and_b32_e32 v129, 0xffff0000, v68
	v_lshlrev_b32_e32 v130, 16, v69
	v_and_b32_e32 v131, 0xffff0000, v69
	v_lshlrev_b32_e32 v132, 16, v70
	v_and_b32_e32 v133, 0xffff0000, v70
	v_lshlrev_b32_e32 v134, 16, v71
	v_and_b32_e32 v135, 0xffff0000, v71
	v_lshlrev_b32_e32 v136, 16, v72
	v_and_b32_e32 v137, 0xffff0000, v72
	v_lshlrev_b32_e32 v138, 16, v73
	v_and_b32_e32 v139, 0xffff0000, v73
	global_load_dwordx2 v[42:43], v3, s[8:9]
	global_load_dwordx2 v[58:59], v2, s[8:9]
	s_add_u32 s8, s8, s10
	s_addc_u32 s9, s9, s11
	global_load_dwordx2 v[44:45], v3, s[8:9]
	global_load_dwordx2 v[60:61], v2, s[8:9]
	s_add_u32 s8, s8, s10
	s_addc_u32 s9, s9, s11
	global_load_dwordx2 v[46:47], v3, s[8:9]
	global_load_dwordx2 v[62:63], v2, s[8:9]
	s_add_u32 s8, s8, s10
	s_addc_u32 s9, s9, s11
	global_load_dwordx2 v[48:49], v3, s[8:9]
	global_load_dwordx2 v[64:65], v2, s[8:9]
	s_add_u32 s8, s8, s10
	s_addc_u32 s9, s9, s11
	global_load_dwordx2 v[50:51], v3, s[8:9]
	global_load_dwordx2 v[66:67], v2, s[8:9]
	s_add_u32 s8, s8, s10
	s_addc_u32 s9, s9, s11
	global_load_dwordx2 v[52:53], v3, s[8:9]
	global_load_dwordx2 v[68:69], v2, s[8:9]
	s_add_u32 s8, s8, s10
	s_addc_u32 s9, s9, s11
	global_load_dwordx2 v[54:55], v3, s[8:9]
	global_load_dwordx2 v[70:71], v2, s[8:9]
	s_add_u32 s8, s8, s10
	s_addc_u32 s9, s9, s11
	global_load_dwordx2 v[56:57], v3, s[8:9]
	global_load_dwordx2 v[72:73], v2, s[8:9]
	s_add_u32 s8, s8, s10
	s_addc_u32 s9, s9, s11
	s_cmp_lt_u32 s16, 63
	s_cselect_b32 s34, s12, s14
	s_cselect_b32 s35, s13, s15
	s_add_u32 s8, s8, s34
	s_addc_u32 s9, s9, s35
	s_add_i32 s16, s16, 1
	v_mov_b32_e32 v176, 1.0
	v_mov_b32_e32 v177, 1.0
	v_mov_b32_e32 v178, 1.0
	v_mov_b32_e32 v179, 1.0
	v_mul_f32_dpp v196, v168, v168 row_ror:8 row_mask:0xf bank_mask:0xf
	v_mul_f32_dpp v197, v169, v169 row_ror:8 row_mask:0xf bank_mask:0xf
	v_mul_f32_dpp v198, v170, v170 row_ror:8 row_mask:0xf bank_mask:0xf
	v_mul_f32_dpp v199, v171, v171 row_ror:8 row_mask:0xf bank_mask:0xf
	v_mov_b32_dpp v176, v168 row_shr:8 row_mask:0xf bank_mask:0xc
	v_mov_b32_dpp v177, v169 row_shr:8 row_mask:0xf bank_mask:0xc
	v_mov_b32_dpp v178, v170 row_shr:8 row_mask:0xf bank_mask:0xc
	v_mov_b32_dpp v179, v171 row_shr:8 row_mask:0xf bank_mask:0xc
	v_mov_b32_e32 v200, v196
	v_mov_b32_e32 v201, v197
	v_mov_b32_e32 v202, v198
	v_mov_b32_e32 v203, v199
	v_permlane16_swap_b32_e32 v196, v200
	v_permlane16_swap_b32_e32 v197, v201
	v_permlane16_swap_b32_e32 v198, v202
	v_permlane16_swap_b32_e32 v199, v203
	v_pk_mul_f32 v[204:205], v[196:197], v[200:201]
	v_pk_mul_f32 v[206:207], v[198:199], v[202:203]
	s_nop 1
	v_permlane32_swap_b32_e32 v200, v204
	v_permlane32_swap_b32_e32 v201, v205
	v_permlane32_swap_b32_e32 v202, v206
	v_permlane32_swap_b32_e32 v203, v207
	s_mov_b64 s[34:35], exec
	s_mov_b64 exec, 0xffff0000
	v_pk_mul_f32 v[176:177], v[176:177], v[196:197]
	v_pk_mul_f32 v[178:179], v[178:179], v[198:199]
	s_mov_b32 exec_lo, 0
	s_mov_b32 exec_hi, -1
	v_pk_mul_f32 v[176:177], v[176:177], v[200:201]
	v_pk_mul_f32 v[178:179], v[178:179], v[202:203]
	s_mov_b32 exec_hi, 0xffff0000
	v_pk_mul_f32 v[176:177], v[176:177], v[196:197]
	v_pk_mul_f32 v[178:179], v[178:179], v[198:199]
	s_mov_b64 exec, s[34:35]
	v_pk_mul_f32 v[188:189], v[176:177], v[168:169]
	v_pk_mul_f32 v[190:191], v[178:179], v[170:171]
	s_mov_b64 s[34:35], exec
	s_mov_b64 exec, s[30:31]
	ds_write_b128 v8, v[188:191] offset:512
	s_mov_b64 exec, s[34:35]
	v_max_f32_e32 v180, 0xda24260, v188
	v_max_f32_e32 v181, 0xda24260, v189
	v_max_f32_e32 v182, 0xda24260, v190
	v_max_f32_e32 v183, 0xda24260, v191
	v_rcp_f32_e32 v180, v180
	v_rcp_f32_e32 v181, v181
	v_rcp_f32_e32 v182, v182
	v_rcp_f32_e32 v183, v183
	v_pk_mul_f32 v[192:193], v[136:137], v[188:189]
	v_pk_mul_f32 v[194:195], v[138:139], v[190:191]
	v_pk_mul_f32 v[196:197], v[104:105], v[180:181]
	v_pk_mul_f32 v[198:199], v[106:107], v[182:183]
	v_cvt_pk_bf16_f32 v208, v192, v193
	v_cvt_pk_bf16_f32 v209, v194, v195
	v_cvt_pk_bf16_f32 v210, v196, v197
	v_cvt_pk_bf16_f32 v211, v198, v199
	v_pk_fma_f32 v[180:181], v[104:105], v[180:181], v[180:181] neg_lo:[1,0,0] neg_hi:[1,0,0]
	v_pk_fma_f32 v[182:183], v[106:107], v[182:183], v[182:183] neg_lo:[1,0,0] neg_hi:[1,0,0]
	v_pk_mul_f32 v[188:189], v[176:177], v[164:165]
	v_pk_mul_f32 v[190:191], v[178:179], v[166:167]
	v_pk_mul_f32 v[192:193], v[132:133], v[188:189]
	v_pk_mul_f32 v[194:195], v[134:135], v[190:191]
	v_pk_mul_f32 v[200:201], v[100:101], v[180:181]
	v_pk_mul_f32 v[202:203], v[102:103], v[182:183]
	v_cvt_pk_bf16_f32 v204, v192, v193
	v_cvt_pk_bf16_f32 v205, v194, v195
	v_cvt_pk_bf16_f32 v206, v200, v201
	v_cvt_pk_bf16_f32 v207, v202, v203
	ds_write2_b64 v6, v[204:205], v[208:209] offset0:216 offset1:252
	ds_write2_b64 v9, v[206:207], v[210:211] offset0:216 offset1:252
	v_pk_fma_f32 v[180:181], v[100:101], v[180:181], v[180:181] neg_lo:[1,0,0] neg_hi:[1,0,0]
	v_pk_fma_f32 v[182:183], v[102:103], v[182:183], v[182:183] neg_lo:[1,0,0] neg_hi:[1,0,0]
	v_pk_mul_f32 v[188:189], v[176:177], v[160:161]
	v_pk_mul_f32 v[190:191], v[178:179], v[162:163]
	v_pk_mul_f32 v[192:193], v[128:129], v[188:189]
	v_pk_mul_f32 v[194:195], v[130:131], v[190:191]
	v_pk_mul_f32 v[196:197], v[96:97], v[180:181]
	v_pk_mul_f32 v[198:199], v[98:99], v[182:183]
	v_cvt_pk_bf16_f32 v208, v192, v193
	v_cvt_pk_bf16_f32 v209, v194, v195
	v_cvt_pk_bf16_f32 v210, v196, v197
	v_cvt_pk_bf16_f32 v211, v198, v199
	v_pk_fma_f32 v[180:181], v[96:97], v[180:181], v[180:181] neg_lo:[1,0,0] neg_hi:[1,0,0]
	v_pk_fma_f32 v[182:183], v[98:99], v[182:183], v[182:183] neg_lo:[1,0,0] neg_hi:[1,0,0]
	v_pk_mul_f32 v[188:189], v[176:177], v[156:157]
	v_pk_mul_f32 v[190:191], v[178:179], v[158:159]
	v_pk_mul_f32 v[192:193], v[124:125], v[188:189]
	v_pk_mul_f32 v[194:195], v[126:127], v[190:191]
	v_pk_mul_f32 v[200:201], v[92:93], v[180:181]
	v_pk_mul_f32 v[202:203], v[94:95], v[182:183]
	v_cvt_pk_bf16_f32 v204, v192, v193
	v_cvt_pk_bf16_f32 v205, v194, v195
	v_cvt_pk_bf16_f32 v206, v200, v201
	v_cvt_pk_bf16_f32 v207, v202, v203
	ds_write2_b64 v6, v[204:205], v[208:209] offset0:144 offset1:180
	ds_write2_b64 v9, v[206:207], v[210:211] offset0:144 offset1:180
	v_pk_fma_f32 v[180:181], v[92:93], v[180:181], v[180:181] neg_lo:[1,0,0] neg_hi:[1,0,0]
	v_pk_fma_f32 v[182:183], v[94:95], v[182:183], v[182:183] neg_lo:[1,0,0] neg_hi:[1,0,0]
	v_pk_mul_f32 v[188:189], v[176:177], v[152:153]
	v_pk_mul_f32 v[190:191], v[178:179], v[154:155]
	v_pk_mul_f32 v[192:193], v[120:121], v[188:189]
	v_pk_mul_f32 v[194:195], v[122:123], v[190:191]
	v_pk_mul_f32 v[196:197], v[88:89], v[180:181]
	v_pk_mul_f32 v[198:199], v[90:91], v[182:183]
	v_cvt_pk_bf16_f32 v208, v192, v193
	v_cvt_pk_bf16_f32 v209, v194, v195
	v_cvt_pk_bf16_f32 v210, v196, v197
	v_cvt_pk_bf16_f32 v211, v198, v199
	v_pk_fma_f32 v[180:181], v[88:89], v[180:181], v[180:181] neg_lo:[1,0,0] neg_hi:[1,0,0]
	v_pk_fma_f32 v[182:183], v[90:91], v[182:183], v[182:183] neg_lo:[1,0,0] neg_hi:[1,0,0]
	v_pk_mul_f32 v[188:189], v[176:177], v[148:149]
	v_pk_mul_f32 v[190:191], v[178:179], v[150:151]
	v_pk_mul_f32 v[192:193], v[116:117], v[188:189]
	v_pk_mul_f32 v[194:195], v[118:119], v[190:191]
	v_pk_mul_f32 v[200:201], v[84:85], v[180:181]
	v_pk_mul_f32 v[202:203], v[86:87], v[182:183]
	v_cvt_pk_bf16_f32 v204, v192, v193
	v_cvt_pk_bf16_f32 v205, v194, v195
	v_cvt_pk_bf16_f32 v206, v200, v201
	v_cvt_pk_bf16_f32 v207, v202, v203
	ds_write2_b64 v6, v[204:205], v[208:209] offset0:72 offset1:108
	ds_write2_b64 v9, v[206:207], v[210:211] offset0:72 offset1:108
	v_pk_fma_f32 v[180:181], v[84:85], v[180:181], v[180:181] neg_lo:[1,0,0] neg_hi:[1,0,0]
	v_pk_fma_f32 v[182:183], v[86:87], v[182:183], v[182:183] neg_lo:[1,0,0] neg_hi:[1,0,0]
	v_pk_mul_f32 v[188:189], v[176:177], v[144:145]
	v_pk_mul_f32 v[190:191], v[178:179], v[146:147]
	v_pk_mul_f32 v[192:193], v[112:113], v[188:189]
	v_pk_mul_f32 v[194:195], v[114:115], v[190:191]
	v_pk_mul_f32 v[196:197], v[80:81], v[180:181]
	v_pk_mul_f32 v[198:199], v[82:83], v[182:183]
	v_cvt_pk_bf16_f32 v208, v192, v193
	v_cvt_pk_bf16_f32 v209, v194, v195
	v_cvt_pk_bf16_f32 v210, v196, v197
	v_cvt_pk_bf16_f32 v211, v198, v199
	v_pk_fma_f32 v[180:181], v[80:81], v[180:181], v[180:181] neg_lo:[1,0,0] neg_hi:[1,0,0]
	v_pk_fma_f32 v[182:183], v[82:83], v[182:183], v[182:183] neg_lo:[1,0,0] neg_hi:[1,0,0]
	v_pk_mul_f32 v[188:189], v[176:177], v[140:141]
	v_pk_mul_f32 v[190:191], v[178:179], v[142:143]
	v_pk_mul_f32 v[192:193], v[108:109], v[188:189]
	v_pk_mul_f32 v[194:195], v[110:111], v[190:191]
	v_pk_mul_f32 v[200:201], v[76:77], v[180:181]
	v_pk_mul_f32 v[202:203], v[78:79], v[182:183]
	v_cvt_pk_bf16_f32 v204, v192, v193
	v_cvt_pk_bf16_f32 v205, v194, v195
	v_cvt_pk_bf16_f32 v206, v200, v201
	v_cvt_pk_bf16_f32 v207, v202, v203
	ds_write2_b64 v6, v[204:205], v[208:209] offset0:0 offset1:36
	ds_write2_b64 v9, v[206:207], v[210:211] offset0:0 offset1:36
	s_waitcnt vmcnt(16)
	v_lshlrev_b32_e32 v76, 16, v10
	v_and_b32_e32 v77, 0xffff0000, v10
	v_lshlrev_b32_e32 v78, 16, v11
	v_and_b32_e32 v79, 0xffff0000, v11
	v_lshlrev_b32_e32 v80, 16, v12
	v_and_b32_e32 v81, 0xffff0000, v12
	v_lshlrev_b32_e32 v82, 16, v13
	v_and_b32_e32 v83, 0xffff0000, v13
	v_lshlrev_b32_e32 v84, 16, v14
	v_and_b32_e32 v85, 0xffff0000, v14
	v_lshlrev_b32_e32 v86, 16, v15
	v_and_b32_e32 v87, 0xffff0000, v15
	v_lshlrev_b32_e32 v88, 16, v16
	v_and_b32_e32 v89, 0xffff0000, v16
	v_lshlrev_b32_e32 v90, 16, v17
	v_and_b32_e32 v91, 0xffff0000, v17
	v_lshlrev_b32_e32 v92, 16, v18
	v_and_b32_e32 v93, 0xffff0000, v18
	v_lshlrev_b32_e32 v94, 16, v19
	v_and_b32_e32 v95, 0xffff0000, v19
	v_lshlrev_b32_e32 v96, 16, v20
	v_and_b32_e32 v97, 0xffff0000, v20
	v_lshlrev_b32_e32 v98, 16, v21
	v_and_b32_e32 v99, 0xffff0000, v21
	v_lshlrev_b32_e32 v100, 16, v22
	v_and_b32_e32 v101, 0xffff0000, v22
	v_lshlrev_b32_e32 v102, 16, v23
	v_and_b32_e32 v103, 0xffff0000, v23
	v_lshlrev_b32_e32 v104, 16, v24
	v_and_b32_e32 v105, 0xffff0000, v24
	v_lshlrev_b32_e32 v106, 16, v25
	v_and_b32_e32 v107, 0xffff0000, v25
	v_pk_add_f32 v[140:141], v[76:77], 1.0 op_sel_hi:[1,0] neg_lo:[1,0] neg_hi:[1,0]
	v_pk_add_f32 v[142:143], v[78:79], 1.0 op_sel_hi:[1,0] neg_lo:[1,0] neg_hi:[1,0]
	v_pk_fma_f32 v[144:145], v[80:81], v[140:141], v[140:141] neg_lo:[1,0,0] neg_hi:[1,0,0]
	v_pk_fma_f32 v[146:147], v[82:83], v[142:143], v[142:143] neg_lo:[1,0,0] neg_hi:[1,0,0]
	v_pk_fma_f32 v[148:149], v[84:85], v[144:145], v[144:145] neg_lo:[1,0,0] neg_hi:[1,0,0]
	v_pk_fma_f32 v[150:151], v[86:87], v[146:147], v[146:147] neg_lo:[1,0,0] neg_hi:[1,0,0]
	v_pk_fma_f32 v[152:153], v[88:89], v[148:149], v[148:149] neg_lo:[1,0,0] neg_hi:[1,0,0]
	v_pk_fma_f32 v[154:155], v[90:91], v[150:151], v[150:151] neg_lo:[1,0,0] neg_hi:[1,0,0]
	v_pk_fma_f32 v[156:157], v[92:93], v[152:153], v[152:153] neg_lo:[1,0,0] neg_hi:[1,0,0]
	v_pk_fma_f32 v[158:159], v[94:95], v[154:155], v[154:155] neg_lo:[1,0,0] neg_hi:[1,0,0]
	v_pk_fma_f32 v[160:161], v[96:97], v[156:157], v[156:157] neg_lo:[1,0,0] neg_hi:[1,0,0]
	v_pk_fma_f32 v[162:163], v[98:99], v[158:159], v[158:159] neg_lo:[1,0,0] neg_hi:[1,0,0]
	v_pk_fma_f32 v[164:165], v[100:101], v[160:161], v[160:161] neg_lo:[1,0,0] neg_hi:[1,0,0]
	v_pk_fma_f32 v[166:167], v[102:103], v[162:163], v[162:163] neg_lo:[1,0,0] neg_hi:[1,0,0]
	v_pk_fma_f32 v[168:169], v[104:105], v[164:165], v[164:165] neg_lo:[1,0,0] neg_hi:[1,0,0]
	v_pk_fma_f32 v[170:171], v[106:107], v[166:167], v[166:167] neg_lo:[1,0,0] neg_hi:[1,0,0]
	s_waitcnt lgkmcnt(0)
	s_barrier
	s_cmp_eq_u32 s17, 0
	s_cbranch_scc1 .Lhg_pend
	v_lshlrev_b32_e32 v108, 16, v26
	v_and_b32_e32 v109, 0xffff0000, v26
	v_lshlrev_b32_e32 v110, 16, v27
	v_and_b32_e32 v111, 0xffff0000, v27
	v_lshlrev_b32_e32 v112, 16, v28
	v_and_b32_e32 v113, 0xffff0000, v28
	v_lshlrev_b32_e32 v114, 16, v29
	v_and_b32_e32 v115, 0xffff0000, v29
	v_lshlrev_b32_e32 v116, 16, v30
	v_and_b32_e32 v117, 0xffff0000, v30
	v_lshlrev_b32_e32 v118, 16, v31
	v_and_b32_e32 v119, 0xffff0000, v31
	v_lshlrev_b32_e32 v120, 16, v32
	v_and_b32_e32 v121, 0xffff0000, v32
	v_lshlrev_b32_e32 v122, 16, v33
	v_and_b32_e32 v123, 0xffff0000, v33
	v_lshlrev_b32_e32 v124, 16, v34
	v_and_b32_e32 v125, 0xffff0000, v34
	v_lshlrev_b32_e32 v126, 16, v35
	v_and_b32_e32 v127, 0xffff0000, v35
	v_lshlrev_b32_e32 v128, 16, v36
	v_and_b32_e32 v129, 0xffff0000, v36
	v_lshlrev_b32_e32 v130, 16, v37
	v_and_b32_e32 v131, 0xffff0000, v37
	v_lshlrev_b32_e32 v132, 16, v38
	v_and_b32_e32 v133, 0xffff0000, v38
	v_lshlrev_b32_e32 v134, 16, v39
	v_and_b32_e32 v135, 0xffff0000, v39
	v_lshlrev_b32_e32 v136, 16, v40
	v_and_b32_e32 v137, 0xffff0000, v40
	v_lshlrev_b32_e32 v138, 16, v41
	v_and_b32_e32 v139, 0xffff0000, v41
	global_load_dwordx2 v[10:11], v3, s[8:9]
	global_load_dwordx2 v[26:27], v2, s[8:9]
	s_add_u32 s8, s8, s10
	s_addc_u32 s9, s9, s11
	global_load_dwordx2 v[12:13], v3, s[8:9]
	global_load_dwordx2 v[28:29], v2, s[8:9]
	s_add_u32 s8, s8, s10
	s_addc_u32 s9, s9, s11
	global_load_dwordx2 v[14:15], v3, s[8:9]
	global_load_dwordx2 v[30:31], v2, s[8:9]
	s_add_u32 s8, s8, s10
	s_addc_u32 s9, s9, s11
	global_load_dwordx2 v[16:17], v3, s[8:9]
	global_load_dwordx2 v[32:33], v2, s[8:9]
	s_add_u32 s8, s8, s10
	s_addc_u32 s9, s9, s11
	global_load_dwordx2 v[18:19], v3, s[8:9]
	global_load_dwordx2 v[34:35], v2, s[8:9]
	s_add_u32 s8, s8, s10
	s_addc_u32 s9, s9, s11
	global_load_dwordx2 v[20:21], v3, s[8:9]
	global_load_dwordx2 v[36:37], v2, s[8:9]
	s_add_u32 s8, s8, s10
	s_addc_u32 s9, s9, s11
	global_load_dwordx2 v[22:23], v3, s[8:9]
	global_load_dwordx2 v[38:39], v2, s[8:9]
	s_add_u32 s8, s8, s10
	s_addc_u32 s9, s9, s11
	global_load_dwordx2 v[24:25], v3, s[8:9]
	global_load_dwordx2 v[40:41], v2, s[8:9]
	s_add_u32 s8, s8, s10
	s_addc_u32 s9, s9, s11
	s_cmp_lt_u32 s16, 63
	s_cselect_b32 s34, s12, s14
	s_cselect_b32 s35, s13, s15
	s_add_u32 s8, s8, s34
	s_addc_u32 s9, s9, s35
	s_add_i32 s16, s16, 1
	v_mov_b32_e32 v176, 1.0
	v_mov_b32_e32 v177, 1.0
	v_mov_b32_e32 v178, 1.0
	v_mov_b32_e32 v179, 1.0
	v_mul_f32_dpp v196, v168, v168 row_ror:8 row_mask:0xf bank_mask:0xf
	v_mul_f32_dpp v197, v169, v169 row_ror:8 row_mask:0xf bank_mask:0xf
	v_mul_f32_dpp v198, v170, v170 row_ror:8 row_mask:0xf bank_mask:0xf
	v_mul_f32_dpp v199, v171, v171 row_ror:8 row_mask:0xf bank_mask:0xf
	v_mov_b32_dpp v176, v168 row_shr:8 row_mask:0xf bank_mask:0xc
	v_mov_b32_dpp v177, v169 row_shr:8 row_mask:0xf bank_mask:0xc
	v_mov_b32_dpp v178, v170 row_shr:8 row_mask:0xf bank_mask:0xc
	v_mov_b32_dpp v179, v171 row_shr:8 row_mask:0xf bank_mask:0xc
	v_mov_b32_e32 v200, v196
	v_mov_b32_e32 v201, v197
	v_mov_b32_e32 v202, v198
	v_mov_b32_e32 v203, v199
	v_permlane16_swap_b32_e32 v196, v200
	v_permlane16_swap_b32_e32 v197, v201
	v_permlane16_swap_b32_e32 v198, v202
	v_permlane16_swap_b32_e32 v199, v203
	v_pk_mul_f32 v[204:205], v[196:197], v[200:201]
	v_pk_mul_f32 v[206:207], v[198:199], v[202:203]
	s_nop 1
	v_permlane32_swap_b32_e32 v200, v204
	v_permlane32_swap_b32_e32 v201, v205
	v_permlane32_swap_b32_e32 v202, v206
	v_permlane32_swap_b32_e32 v203, v207
	s_mov_b64 s[34:35], exec
	s_mov_b64 exec, 0xffff0000
	v_pk_mul_f32 v[176:177], v[176:177], v[196:197]
	v_pk_mul_f32 v[178:179], v[178:179], v[198:199]
	s_mov_b32 exec_lo, 0
	s_mov_b32 exec_hi, -1
	v_pk_mul_f32 v[176:177], v[176:177], v[200:201]
	v_pk_mul_f32 v[178:179], v[178:179], v[202:203]
	s_mov_b32 exec_hi, 0xffff0000
	v_pk_mul_f32 v[176:177], v[176:177], v[196:197]
	v_pk_mul_f32 v[178:179], v[178:179], v[198:199]
	s_mov_b64 exec, s[34:35]
	v_pk_mul_f32 v[188:189], v[176:177], v[168:169]
	v_pk_mul_f32 v[190:191], v[178:179], v[170:171]
	s_mov_b64 s[34:35], exec
	s_mov_b64 exec, s[30:31]
	ds_write_b128 v8, v[188:191]
	s_mov_b64 exec, s[34:35]
	v_max_f32_e32 v180, 0xda24260, v188
	v_max_f32_e32 v181, 0xda24260, v189
	v_max_f32_e32 v182, 0xda24260, v190
	v_max_f32_e32 v183, 0xda24260, v191
	v_rcp_f32_e32 v180, v180
	v_rcp_f32_e32 v181, v181
	v_rcp_f32_e32 v182, v182
	v_rcp_f32_e32 v183, v183
	v_pk_mul_f32 v[192:193], v[136:137], v[188:189]
	v_pk_mul_f32 v[194:195], v[138:139], v[190:191]
	v_pk_mul_f32 v[196:197], v[104:105], v[180:181]
	v_pk_mul_f32 v[198:199], v[106:107], v[182:183]
	v_cvt_pk_bf16_f32 v208, v192, v193
	v_cvt_pk_bf16_f32 v209, v194, v195
	v_cvt_pk_bf16_f32 v210, v196, v197
	v_cvt_pk_bf16_f32 v211, v198, v199
	v_pk_fma_f32 v[180:181], v[104:105], v[180:181], v[180:181] neg_lo:[1,0,0] neg_hi:[1,0,0]
	v_pk_fma_f32 v[182:183], v[106:107], v[182:183], v[182:183] neg_lo:[1,0,0] neg_hi:[1,0,0]
	v_pk_mul_f32 v[188:189], v[176:177], v[164:165]
	v_pk_mul_f32 v[190:191], v[178:179], v[166:167]
	v_pk_mul_f32 v[192:193], v[132:133], v[188:189]
	v_pk_mul_f32 v[194:195], v[134:135], v[190:191]
	v_pk_mul_f32 v[200:201], v[100:101], v[180:181]
	v_pk_mul_f32 v[202:203], v[102:103], v[182:183]
	v_cvt_pk_bf16_f32 v204, v192, v193
	v_cvt_pk_bf16_f32 v205, v194, v195
	v_cvt_pk_bf16_f32 v206, v200, v201
	v_cvt_pk_bf16_f32 v207, v202, v203
	ds_write2_b64 v4, v[204:205], v[208:209] offset0:216 offset1:252
	ds_write2_b64 v7, v[206:207], v[210:211] offset0:216 offset1:252
	v_pk_fma_f32 v[180:181], v[100:101], v[180:181], v[180:181] neg_lo:[1,0,0] neg_hi:[1,0,0]
	v_pk_fma_f32 v[182:183], v[102:103], v[182:183], v[182:183] neg_lo:[1,0,0] neg_hi:[1,0,0]
	v_pk_mul_f32 v[188:189], v[176:177], v[160:161]
	v_pk_mul_f32 v[190:191], v[178:179], v[162:163]
	v_pk_mul_f32 v[192:193], v[128:129], v[188:189]
	v_pk_mul_f32 v[194:195], v[130:131], v[190:191]
	v_pk_mul_f32 v[196:197], v[96:97], v[180:181]
	v_pk_mul_f32 v[198:199], v[98:99], v[182:183]
	v_cvt_pk_bf16_f32 v208, v192, v193
	v_cvt_pk_bf16_f32 v209, v194, v195
	v_cvt_pk_bf16_f32 v210, v196, v197
	v_cvt_pk_bf16_f32 v211, v198, v199
	v_pk_fma_f32 v[180:181], v[96:97], v[180:181], v[180:181] neg_lo:[1,0,0] neg_hi:[1,0,0]
	v_pk_fma_f32 v[182:183], v[98:99], v[182:183], v[182:183] neg_lo:[1,0,0] neg_hi:[1,0,0]
	v_pk_mul_f32 v[188:189], v[176:177], v[156:157]
	v_pk_mul_f32 v[190:191], v[178:179], v[158:159]
	v_pk_mul_f32 v[192:193], v[124:125], v[188:189]
	v_pk_mul_f32 v[194:195], v[126:127], v[190:191]
	v_pk_mul_f32 v[200:201], v[92:93], v[180:181]
	v_pk_mul_f32 v[202:203], v[94:95], v[182:183]
	v_cvt_pk_bf16_f32 v204, v192, v193
	v_cvt_pk_bf16_f32 v205, v194, v195
	v_cvt_pk_bf16_f32 v206, v200, v201
	v_cvt_pk_bf16_f32 v207, v202, v203
	ds_write2_b64 v4, v[204:205], v[208:209] offset0:144 offset1:180
	ds_write2_b64 v7, v[206:207], v[210:211] offset0:144 offset1:180
	v_pk_fma_f32 v[180:181], v[92:93], v[180:181], v[180:181] neg_lo:[1,0,0] neg_hi:[1,0,0]
	v_pk_fma_f32 v[182:183], v[94:95], v[182:183], v[182:183] neg_lo:[1,0,0] neg_hi:[1,0,0]
	v_pk_mul_f32 v[188:189], v[176:177], v[152:153]
	v_pk_mul_f32 v[190:191], v[178:179], v[154:155]
	v_pk_mul_f32 v[192:193], v[120:121], v[188:189]
	v_pk_mul_f32 v[194:195], v[122:123], v[190:191]
	v_pk_mul_f32 v[196:197], v[88:89], v[180:181]
	v_pk_mul_f32 v[198:199], v[90:91], v[182:183]
	v_cvt_pk_bf16_f32 v208, v192, v193
	v_cvt_pk_bf16_f32 v209, v194, v195
	v_cvt_pk_bf16_f32 v210, v196, v197
	v_cvt_pk_bf16_f32 v211, v198, v199
	v_pk_fma_f32 v[180:181], v[88:89], v[180:181], v[180:181] neg_lo:[1,0,0] neg_hi:[1,0,0]
	v_pk_fma_f32 v[182:183], v[90:91], v[182:183], v[182:183] neg_lo:[1,0,0] neg_hi:[1,0,0]
	v_pk_mul_f32 v[188:189], v[176:177], v[148:149]
	v_pk_mul_f32 v[190:191], v[178:179], v[150:151]
	v_pk_mul_f32 v[192:193], v[116:117], v[188:189]
	v_pk_mul_f32 v[194:195], v[118:119], v[190:191]
	v_pk_mul_f32 v[200:201], v[84:85], v[180:181]
	v_pk_mul_f32 v[202:203], v[86:87], v[182:183]
	v_cvt_pk_bf16_f32 v204, v192, v193
	v_cvt_pk_bf16_f32 v205, v194, v195
	v_cvt_pk_bf16_f32 v206, v200, v201
	v_cvt_pk_bf16_f32 v207, v202, v203
	ds_write2_b64 v4, v[204:205], v[208:209] offset0:72 offset1:108
	ds_write2_b64 v7, v[206:207], v[210:211] offset0:72 offset1:108
	v_pk_fma_f32 v[180:181], v[84:85], v[180:181], v[180:181] neg_lo:[1,0,0] neg_hi:[1,0,0]
	v_pk_fma_f32 v[182:183], v[86:87], v[182:183], v[182:183] neg_lo:[1,0,0] neg_hi:[1,0,0]
	v_pk_mul_f32 v[188:189], v[176:177], v[144:145]
	v_pk_mul_f32 v[190:191], v[178:179], v[146:147]
	v_pk_mul_f32 v[192:193], v[112:113], v[188:189]
	v_pk_mul_f32 v[194:195], v[114:115], v[190:191]
	v_pk_mul_f32 v[196:197], v[80:81], v[180:181]
	v_pk_mul_f32 v[198:199], v[82:83], v[182:183]
	v_cvt_pk_bf16_f32 v208, v192, v193
	v_cvt_pk_bf16_f32 v209, v194, v195
	v_cvt_pk_bf16_f32 v210, v196, v197
	v_cvt_pk_bf16_f32 v211, v198, v199
	v_pk_fma_f32 v[180:181], v[80:81], v[180:181], v[180:181] neg_lo:[1,0,0] neg_hi:[1,0,0]
	v_pk_fma_f32 v[182:183], v[82:83], v[182:183], v[182:183] neg_lo:[1,0,0] neg_hi:[1,0,0]
	v_pk_mul_f32 v[188:189], v[176:177], v[140:141]
	v_pk_mul_f32 v[190:191], v[178:179], v[142:143]
	v_pk_mul_f32 v[192:193], v[108:109], v[188:189]
	v_pk_mul_f32 v[194:195], v[110:111], v[190:191]
	v_pk_mul_f32 v[200:201], v[76:77], v[180:181]
	v_pk_mul_f32 v[202:203], v[78:79], v[182:183]
	v_cvt_pk_bf16_f32 v204, v192, v193
	v_cvt_pk_bf16_f32 v205, v194, v195
	v_cvt_pk_bf16_f32 v206, v200, v201
	v_cvt_pk_bf16_f32 v207, v202, v203
	ds_write2_b64 v4, v[204:205], v[208:209] offset0:0 offset1:36
	ds_write2_b64 v7, v[206:207], v[210:211] offset0:0 offset1:36
	s_waitcnt vmcnt(16)
	v_lshlrev_b32_e32 v76, 16, v42
	v_and_b32_e32 v77, 0xffff0000, v42
	v_lshlrev_b32_e32 v78, 16, v43
	v_and_b32_e32 v79, 0xffff0000, v43
	v_lshlrev_b32_e32 v80, 16, v44
	v_and_b32_e32 v81, 0xffff0000, v44
	v_lshlrev_b32_e32 v82, 16, v45
	v_and_b32_e32 v83, 0xffff0000, v45
	v_lshlrev_b32_e32 v84, 16, v46
	v_and_b32_e32 v85, 0xffff0000, v46
	v_lshlrev_b32_e32 v86, 16, v47
	v_and_b32_e32 v87, 0xffff0000, v47
	v_lshlrev_b32_e32 v88, 16, v48
	v_and_b32_e32 v89, 0xffff0000, v48
	v_lshlrev_b32_e32 v90, 16, v49
	v_and_b32_e32 v91, 0xffff0000, v49
	v_lshlrev_b32_e32 v92, 16, v50
	v_and_b32_e32 v93, 0xffff0000, v50
	v_lshlrev_b32_e32 v94, 16, v51
	v_and_b32_e32 v95, 0xffff0000, v51
	v_lshlrev_b32_e32 v96, 16, v52
	v_and_b32_e32 v97, 0xffff0000, v52
	v_lshlrev_b32_e32 v98, 16, v53
	v_and_b32_e32 v99, 0xffff0000, v53
	v_lshlrev_b32_e32 v100, 16, v54
	v_and_b32_e32 v101, 0xffff0000, v54
	v_lshlrev_b32_e32 v102, 16, v55
	v_and_b32_e32 v103, 0xffff0000, v55
	v_lshlrev_b32_e32 v104, 16, v56
	v_and_b32_e32 v105, 0xffff0000, v56
	v_lshlrev_b32_e32 v106, 16, v57
	v_and_b32_e32 v107, 0xffff0000, v57
	v_pk_add_f32 v[140:141], v[76:77], 1.0 op_sel_hi:[1,0] neg_lo:[1,0] neg_hi:[1,0]
	v_pk_add_f32 v[142:143], v[78:79], 1.0 op_sel_hi:[1,0] neg_lo:[1,0] neg_hi:[1,0]
	v_pk_fma_f32 v[144:145], v[80:81], v[140:141], v[140:141] neg_lo:[1,0,0] neg_hi:[1,0,0]
	v_pk_fma_f32 v[146:147], v[82:83], v[142:143], v[142:143] neg_lo:[1,0,0] neg_hi:[1,0,0]
	v_pk_fma_f32 v[148:149], v[84:85], v[144:145], v[144:145] neg_lo:[1,0,0] neg_hi:[1,0,0]
	v_pk_fma_f32 v[150:151], v[86:87], v[146:147], v[146:147] neg_lo:[1,0,0] neg_hi:[1,0,0]
	v_pk_fma_f32 v[152:153], v[88:89], v[148:149], v[148:149] neg_lo:[1,0,0] neg_hi:[1,0,0]
	v_pk_fma_f32 v[154:155], v[90:91], v[150:151], v[150:151] neg_lo:[1,0,0] neg_hi:[1,0,0]
	v_pk_fma_f32 v[156:157], v[92:93], v[152:153], v[152:153] neg_lo:[1,0,0] neg_hi:[1,0,0]
	v_pk_fma_f32 v[158:159], v[94:95], v[154:155], v[154:155] neg_lo:[1,0,0] neg_hi:[1,0,0]
	v_pk_fma_f32 v[160:161], v[96:97], v[156:157], v[156:157] neg_lo:[1,0,0] neg_hi:[1,0,0]
	v_pk_fma_f32 v[162:163], v[98:99], v[158:159], v[158:159] neg_lo:[1,0,0] neg_hi:[1,0,0]
	v_pk_fma_f32 v[164:165], v[100:101], v[160:161], v[160:161] neg_lo:[1,0,0] neg_hi:[1,0,0]
	v_pk_fma_f32 v[166:167], v[102:103], v[162:163], v[162:163] neg_lo:[1,0,0] neg_hi:[1,0,0]
	v_pk_fma_f32 v[168:169], v[104:105], v[164:165], v[164:165] neg_lo:[1,0,0] neg_hi:[1,0,0]
	v_pk_fma_f32 v[170:171], v[106:107], v[166:167], v[166:167] neg_lo:[1,0,0] neg_hi:[1,0,0]
	s_waitcnt lgkmcnt(0)
	s_barrier
	s_add_i32 s17, s17, -1
	s_branch .Lhg_ploop
